# MLA attention loop: late softmax half-parts moved into the VALU-free QK gaps, scalar row-sum adds with fixed home, row-max tail spread into last PV gaps (removes the hazard nop)
# speedup vs baseline: 1.0096x; 1.0096x over previous
.LBB0_287:
	v_lshl_add_u64 v[50:51], s[80:81], 0, v[222:223]
	global_load_dwordx4 v[178:181], v[50:51], off
	s_waitcnt lgkmcnt(3)
	v_mfma_f32_32x32x16_bf16 v[50:65], v[68:71], v[166:169], v[34:49]
	v_exp_f32_e32 v72, v114
	v_exp_f32_e32 v73, v115
	ds_read_b128 v[90:93], v254 offset:2048
	ds_read_b128 v[94:97], v254 offset:2560
	v_exp_f32_e32 v74, v130
	v_exp_f32_e32 v75, v131
	v_pk_add_f32 v[66:67], v[66:67], v[72:73]
	v_cvt_pk_bf16_f32 v114, v72, v73
	v_cvt_pk_bf16_f32 v84, v74, v75
	s_nop 0
	v_pk_add_f32 v[130:131], v[74:75], v[66:67]
	s_waitcnt lgkmcnt(4)
	v_mfma_f32_32x32x16_bf16 v[66:81], v[86:89], v[166:169], v[34:49]
	v_exp_f32_e32 v86, v116
	v_exp_f32_e32 v87, v117
	v_exp_f32_e32 v88, v132
	v_exp_f32_e32 v89, v133
	v_cvt_pk_bf16_f32 v115, v86, v87
	v_pk_add_f32 v[116:117], v[86:87], v[130:131]
	v_cvt_pk_bf16_f32 v85, v88, v89
	s_nop 0
	v_pk_add_f32 v[116:117], v[88:89], v[116:117]
	s_waitcnt lgkmcnt(1)
	v_mfma_f32_32x32x16_bf16 v[50:65], v[90:93], v[162:165], v[50:65]
	ds_read_b128 v[130:133], v254 offset:4096
	ds_read_b128 v[190:193], v254 offset:4608
	v_exp_f32_e32 v86, v118
	v_exp_f32_e32 v87, v119
	v_exp_f32_e32 v88, v134
	v_exp_f32_e32 v89, v135
	v_pk_add_f32 v[90:91], v[86:87], v[116:117]
	v_cvt_pk_bf16_f32 v116, v86, v87
	s_nop 0
	v_pk_add_f32 v[90:91], v[88:89], v[90:91]
	v_cvt_pk_bf16_f32 v86, v88, v89
	s_waitcnt lgkmcnt(2)
	v_mfma_f32_32x32x16_bf16 v[66:81], v[94:97], v[162:165], v[66:81]
	v_exp_f32_e32 v88, v120
	v_exp_f32_e32 v89, v121
	v_exp_f32_e32 v92, v136
	v_exp_f32_e32 v93, v137
	v_cvt_pk_bf16_f32 v117, v88, v89
	v_pk_add_f32 v[90:91], v[88:89], v[90:91]
	v_cvt_pk_bf16_f32 v87, v92, v93
	s_nop 0
	v_pk_add_f32 v[96:97], v[92:93], v[90:91]
	s_waitcnt lgkmcnt(1)
	v_mfma_f32_32x32x16_bf16 v[50:65], v[130:133], v[158:161], v[50:65]
	ds_read_b128 v[88:91], v254 offset:6144
	ds_read_b128 v[92:95], v254 offset:6656
	v_exp_f32_e32 v118, v122
	v_exp_f32_e32 v119, v123
	v_exp_f32_e32 v120, v138
	v_exp_f32_e32 v121, v139
	v_pk_add_f32 v[96:97], v[118:119], v[96:97]
	v_cvt_pk_bf16_f32 v118, v118, v119
	s_nop 0
	v_pk_add_f32 v[96:97], v[120:121], v[96:97]
	v_cvt_pk_bf16_f32 v122, v120, v121
	s_waitcnt lgkmcnt(2)
	v_mfma_f32_32x32x16_bf16 v[66:81], v[190:193], v[158:161], v[66:81]
	v_exp_f32_e32 v120, v124
	v_exp_f32_e32 v121, v125
	v_add_f32_e32 v130, v96, v120
	v_cvt_pk_bf16_f32 v119, v120, v121
	v_add_f32_e32 v131, v97, v121
	s_waitcnt lgkmcnt(1)
	v_mfma_f32_32x32x16_bf16 v[50:65], v[88:91], v[154:157], v[50:65]
	ds_read_b128 v[132:135], v254 offset:8192
	ds_read_b128 v[136:139], v254 offset:8704
	v_exp_f32_e32 v88, v126
	v_exp_f32_e32 v89, v127
	v_add_f32_e32 v130, v130, v88
	v_cvt_pk_bf16_f32 v120, v88, v89
	v_add_f32_e32 v131, v131, v89
	s_waitcnt lgkmcnt(2)
	v_mfma_f32_32x32x16_bf16 v[66:81], v[92:95], v[154:157], v[66:81]
	v_exp_f32_e32 v88, v128
	v_exp_f32_e32 v89, v129
	v_add_f32_e32 v130, v130, v88
	v_cvt_pk_bf16_f32 v121, v88, v89
	v_add_f32_e32 v131, v131, v89
	s_waitcnt lgkmcnt(1)
	v_mfma_f32_32x32x16_bf16 v[50:65], v[132:135], v[150:153], v[50:65]
	ds_read_b128 v[88:91], v254 offset:10240
	ds_read_b128 v[92:95], v254 offset:10752
	s_waitcnt lgkmcnt(2)
	v_mfma_f32_32x32x16_bf16 v[66:81], v[136:139], v[150:153], v[66:81]
	v_exp_f32_e32 v140, v140
	v_exp_f32_e32 v141, v141
	v_add_f32_e32 v130, v130, v140
	v_cvt_pk_bf16_f32 v123, v140, v141
	v_add_f32_e32 v131, v131, v141
	s_waitcnt lgkmcnt(1)
	v_mfma_f32_32x32x16_bf16 v[50:65], v[88:91], v[146:149], v[50:65]
	v_exp_f32_e32 v142, v142
	v_exp_f32_e32 v143, v143
	v_add_f32_e32 v130, v130, v142
	v_cvt_pk_bf16_f32 v124, v142, v143
	v_add_f32_e32 v131, v131, v143
	s_waitcnt lgkmcnt(0)
	v_mfma_f32_32x32x16_bf16 v[66:81], v[92:95], v[146:149], v[66:81]
	ds_read_b64_tr_b16 v[88:89], v243 offset:40960
	ds_read_b64_tr_b16 v[90:91], v243 offset:41472
	ds_read_b64_tr_b16 v[92:93], v243 offset:45056
	ds_read_b64_tr_b16 v[94:95], v243 offset:45568
	v_exp_f32_e32 v144, v144
	v_exp_f32_e32 v145, v145
	v_add_f32_e32 v130, v130, v144
	v_cvt_pk_bf16_f32 v125, v144, v145
	v_add_f32_e32 v131, v131, v145
	s_waitcnt lgkmcnt(2)
	v_mfma_f32_32x32x16_bf16 v[18:33], v[114:117], v[88:91], v[18:33]
	ds_read_b64_tr_b16 v[126:127], v243 offset:41984
	ds_read_b64_tr_b16 v[128:129], v243 offset:42496
	v_max_f32_e32 v83, v50, v50
	v_max_f32_e32 v83, 0xf149f2ca, v83
	v_max3_f32 v96, v66, s25, v67
	s_waitcnt lgkmcnt(2)
	v_mfma_f32_32x32x16_bf16 v[2:17], v[114:117], v[92:95], v[2:17]
	ds_read_b64_tr_b16 v[88:89], v243 offset:46080
	ds_read_b64_tr_b16 v[90:91], v243 offset:46592
	v_max3_f32 v83, v83, v51, v52
	v_max3_f32 v96, v96, v68, v69
	s_waitcnt lgkmcnt(2)
	v_mfma_f32_32x32x16_bf16 v[18:33], v[118:121], v[126:129], v[18:33]
	ds_read_b64_tr_b16 v[92:93], v243 offset:43008
	ds_read_b64_tr_b16 v[94:95], v243 offset:43520
	v_max3_f32 v83, v83, v53, v54
	v_max3_f32 v96, v96, v70, v71
	s_waitcnt lgkmcnt(2)
	v_mfma_f32_32x32x16_bf16 v[2:17], v[118:121], v[88:91], v[2:17]
	ds_read_b64_tr_b16 v[114:115], v243 offset:47104
	ds_read_b64_tr_b16 v[116:117], v243 offset:47616
	v_max3_f32 v83, v83, v55, v56
	v_max3_f32 v96, v96, v72, v73
	s_waitcnt lgkmcnt(2)
	v_mfma_f32_32x32x16_bf16 v[18:33], v[84:87], v[92:95], v[18:33]
	ds_read_b64_tr_b16 v[88:89], v243 offset:44032
	ds_read_b64_tr_b16 v[90:91], v243 offset:44544
	v_max3_f32 v83, v83, v57, v58
	v_max3_f32 v96, v96, v74, v75
	s_waitcnt lgkmcnt(2)
	v_mfma_f32_32x32x16_bf16 v[2:17], v[84:87], v[114:117], v[2:17]
	ds_read_b64_tr_b16 v[92:93], v243 offset:48128
	ds_read_b64_tr_b16 v[94:95], v243 offset:48640
	v_max3_f32 v83, v83, v59, v60
	v_max3_f32 v96, v96, v76, v77
	s_waitcnt lgkmcnt(2)
	v_mfma_f32_32x32x16_bf16 v[18:33], v[122:125], v[88:91], v[18:33]
	v_max3_f32 v83, v83, v61, v62
	v_max3_f32 v96, v96, v78, v79
	s_waitcnt lgkmcnt(0)
	v_mfma_f32_32x32x16_bf16 v[2:17], v[122:125], v[92:95], v[2:17]
	v_max3_f32 v83, v83, v63, v64
	v_max3_f32 v96, v96, v80, v81
	s_add_i32 s36, s36, 2
	v_max3_f32 v83, v83, v65, v96
	v_lshl_add_u64 v[218:219], v[218:219], 0, s[38:39]
	v_lshl_add_u64 v[220:221], v[220:221], 0, s[82:83]
	v_lshl_add_u64 v[222:223], v[222:223], 0, s[82:83]
	s_cmpk_gt_u32 s36, 0x7d
	v_lshl_add_u64 v[224:225], v[224:225], 0, s[82:83]
	s_barrier
	s_cbranch_scc1 .LBB0_305

.LBB0_295:
	v_lshl_add_u64 v[114:115], s[80:81], 0, v[224:225]
	global_load_dwordx4 v[178:181], v[114:115], off
	s_waitcnt lgkmcnt(3)
	v_mfma_f32_32x32x16_bf16 v[114:129], v[84:87], v[166:169], v[34:49]
	ds_read_b128 v[92:95], v254 offset:14336
	ds_read_b128 v[190:193], v254 offset:14848
	v_exp_f32_e32 v50, v50
	v_exp_f32_e32 v51, v51
	v_exp_f32_e32 v66, v66
	v_exp_f32_e32 v67, v67
	v_pk_add_f32 v[84:85], v[130:131], v[50:51]
	s_nop 0
	v_pk_add_f32 v[86:87], v[66:67], v[84:85]
	v_cvt_pk_bf16_f32 v84, v50, v51
	v_cvt_pk_bf16_f32 v50, v66, v67
	s_waitcnt lgkmcnt(4)
	v_mfma_f32_32x32x16_bf16 v[130:145], v[88:91], v[166:169], v[34:49]
	v_exp_f32_e32 v52, v52
	v_exp_f32_e32 v53, v53
	v_exp_f32_e32 v66, v68
	v_exp_f32_e32 v67, v69
	v_cvt_pk_bf16_f32 v85, v52, v53
	v_pk_add_f32 v[68:69], v[52:53], v[86:87]
	v_cvt_pk_bf16_f32 v51, v66, v67
	s_nop 0
	v_pk_add_f32 v[86:87], v[66:67], v[68:69]
	s_waitcnt lgkmcnt(1)
	v_mfma_f32_32x32x16_bf16 v[114:129], v[92:95], v[162:165], v[114:129]
	ds_read_b128 v[66:69], v254 offset:16384
	ds_read_b128 v[88:91], v254 offset:16896
	v_exp_f32_e32 v52, v54
	v_exp_f32_e32 v53, v55
	v_exp_f32_e32 v54, v70
	v_exp_f32_e32 v55, v71
	v_pk_add_f32 v[70:71], v[52:53], v[86:87]
	v_cvt_pk_bf16_f32 v86, v52, v53
	s_nop 0
	v_pk_add_f32 v[70:71], v[54:55], v[70:71]
	v_cvt_pk_bf16_f32 v52, v54, v55
	s_waitcnt lgkmcnt(2)
	v_mfma_f32_32x32x16_bf16 v[130:145], v[190:193], v[162:165], v[130:145]
	v_exp_f32_e32 v54, v56
	v_exp_f32_e32 v55, v57
	v_exp_f32_e32 v56, v72
	v_exp_f32_e32 v57, v73
	v_cvt_pk_bf16_f32 v87, v54, v55
	v_pk_add_f32 v[70:71], v[54:55], v[70:71]
	v_cvt_pk_bf16_f32 v53, v56, v57
	s_nop 0
	v_pk_add_f32 v[92:93], v[56:57], v[70:71]
	s_waitcnt lgkmcnt(1)
	v_mfma_f32_32x32x16_bf16 v[114:129], v[66:69], v[158:161], v[114:129]
	ds_read_b128 v[54:57], v254 offset:18432
	ds_read_b128 v[70:73], v254 offset:18944
	v_exp_f32_e32 v58, v58
	v_exp_f32_e32 v59, v59
	v_add_f32_e32 v66, v92, v58
	v_cvt_pk_bf16_f32 v58, v58, v59
	v_add_f32_e32 v67, v93, v59
	s_waitcnt lgkmcnt(2)
	v_mfma_f32_32x32x16_bf16 v[130:145], v[88:91], v[158:161], v[130:145]
	v_exp_f32_e32 v60, v60
	v_exp_f32_e32 v61, v61
	v_add_f32_e32 v66, v66, v60
	v_cvt_pk_bf16_f32 v59, v60, v61
	v_add_f32_e32 v67, v67, v61
	s_waitcnt lgkmcnt(1)
	v_mfma_f32_32x32x16_bf16 v[114:129], v[54:57], v[154:157], v[114:129]
	ds_read_b128 v[88:91], v254 offset:20480
	ds_read_b128 v[92:95], v254 offset:20992
	v_exp_f32_e32 v62, v62
	v_exp_f32_e32 v63, v63
	v_add_f32_e32 v66, v66, v62
	v_cvt_pk_bf16_f32 v60, v62, v63
	v_add_f32_e32 v67, v67, v63
	s_waitcnt lgkmcnt(2)
	v_mfma_f32_32x32x16_bf16 v[130:145], v[70:73], v[154:157], v[130:145]
	v_exp_f32_e32 v64, v64
	v_exp_f32_e32 v65, v65
	v_add_f32_e32 v66, v66, v64
	v_cvt_pk_bf16_f32 v61, v64, v65
	v_add_f32_e32 v67, v67, v65
	s_waitcnt lgkmcnt(1)
	v_mfma_f32_32x32x16_bf16 v[114:129], v[88:91], v[150:153], v[114:129]
	ds_read_b128 v[54:57], v254 offset:22528
	ds_read_b128 v[62:65], v254 offset:23040
	v_exp_f32_e32 v74, v74
	v_exp_f32_e32 v75, v75
	v_add_f32_e32 v66, v66, v74
	v_cvt_pk_bf16_f32 v74, v74, v75
	v_add_f32_e32 v67, v67, v75
	s_waitcnt lgkmcnt(2)
	v_mfma_f32_32x32x16_bf16 v[130:145], v[92:95], v[150:153], v[130:145]
	v_exp_f32_e32 v76, v76
	v_exp_f32_e32 v77, v77
	v_add_f32_e32 v66, v66, v76
	v_cvt_pk_bf16_f32 v75, v76, v77
	v_add_f32_e32 v67, v67, v77
	s_waitcnt lgkmcnt(1)
	v_mfma_f32_32x32x16_bf16 v[114:129], v[54:57], v[146:149], v[114:129]
	v_exp_f32_e32 v78, v78
	v_exp_f32_e32 v79, v79
	v_add_f32_e32 v66, v66, v78
	v_cvt_pk_bf16_f32 v76, v78, v79
	v_add_f32_e32 v67, v67, v79
	s_waitcnt lgkmcnt(0)
	v_mfma_f32_32x32x16_bf16 v[130:145], v[62:65], v[146:149], v[130:145]
	ds_read_b64_tr_b16 v[54:55], v243 offset:24576
	ds_read_b64_tr_b16 v[56:57], v243 offset:25088
	ds_read_b64_tr_b16 v[62:63], v243 offset:28672
	ds_read_b64_tr_b16 v[64:65], v243 offset:29184
	v_exp_f32_e32 v80, v80
	v_exp_f32_e32 v81, v81
	v_add_f32_e32 v66, v66, v80
	v_cvt_pk_bf16_f32 v77, v80, v81
	v_add_f32_e32 v67, v67, v81
	s_waitcnt lgkmcnt(2)
	v_mfma_f32_32x32x16_bf16 v[18:33], v[84:87], v[54:57], v[18:33]
	ds_read_b64_tr_b16 v[68:69], v243 offset:25600
	ds_read_b64_tr_b16 v[70:71], v243 offset:26112
	v_max_f32_e32 v72, v114, v114
	v_max_f32_e32 v72, 0xf149f2ca, v72
	v_max3_f32 v73, v130, s25, v131
	s_waitcnt lgkmcnt(2)
	v_mfma_f32_32x32x16_bf16 v[2:17], v[84:87], v[62:65], v[2:17]
	ds_read_b64_tr_b16 v[54:55], v243 offset:29696
	ds_read_b64_tr_b16 v[56:57], v243 offset:30208
	v_max3_f32 v72, v72, v115, v116
	v_max3_f32 v73, v73, v132, v133
	s_waitcnt lgkmcnt(2)
	v_mfma_f32_32x32x16_bf16 v[18:33], v[58:61], v[68:71], v[18:33]
	ds_read_b64_tr_b16 v[62:63], v243 offset:26624
	ds_read_b64_tr_b16 v[64:65], v243 offset:27136
	v_max3_f32 v72, v72, v117, v118
	v_max3_f32 v73, v73, v134, v135
	s_waitcnt lgkmcnt(2)
	v_mfma_f32_32x32x16_bf16 v[2:17], v[58:61], v[54:57], v[2:17]
	ds_read_b64_tr_b16 v[68:69], v243 offset:30720
	ds_read_b64_tr_b16 v[70:71], v243 offset:31232
	v_max3_f32 v58, v72, v119, v120
	v_max3_f32 v59, v73, v136, v137
	s_waitcnt lgkmcnt(2)
	v_mfma_f32_32x32x16_bf16 v[18:33], v[50:53], v[62:65], v[18:33]
	ds_read_b64_tr_b16 v[54:55], v243 offset:27648
	ds_read_b64_tr_b16 v[56:57], v243 offset:28160
	v_max3_f32 v62, v58, v121, v122
	v_max3_f32 v63, v59, v138, v139
	s_waitcnt lgkmcnt(2)
	v_mfma_f32_32x32x16_bf16 v[2:17], v[50:53], v[68:71], v[2:17]
	ds_read_b64_tr_b16 v[58:59], v243 offset:31744
	ds_read_b64_tr_b16 v[60:61], v243 offset:32256
	v_max3_f32 v62, v62, v123, v124
	v_max3_f32 v63, v63, v140, v141
	s_waitcnt lgkmcnt(2)
	v_mfma_f32_32x32x16_bf16 v[18:33], v[74:77], v[54:57], v[18:33]
	v_max3_f32 v62, v62, v125, v126
	v_max3_f32 v63, v63, v142, v143
	s_waitcnt lgkmcnt(0)
	v_mfma_f32_32x32x16_bf16 v[2:17], v[74:77], v[58:61], v[2:17]
	v_max3_f32 v62, v62, v127, v128
	v_max3_f32 v63, v63, v144, v145
	v_max3_f32 v50, v62, v129, v63
	v_cmp_lt_f32_e32 vcc, s16, v50
	s_barrier
	s_cbranch_vccz .LBB0_299
	ds_bpermute_b32 v34, v251, v50
	s_waitcnt lgkmcnt(0)
	v_max3_f32 v35, v50, v34, 0
	v_exp_f32_e64 v34, -v35
	s_and_saveexec_b64 s[12:13], s[6:7]
	ds_write_b32 v209, v34 offset:57344
	s_or_b64 exec, exec, s[12:13]
	ds_read_b128 v[36:39], v207 offset:57408
	ds_read_b128 v[40:43], v207 offset:57440
	ds_read_b128 v[44:47], v207 offset:57344
	ds_read_b128 v[48:51], v207 offset:57376
	v_add_f32_e32 v229, v229, v35
	v_xor_b32_e32 v82, 0x80000000, v229
	v_mov_b32_e32 v83, v82
	v_sub_f32_e32 v129, v129, v35
	v_sub_f32_e32 v128, v128, v35
	v_sub_f32_e32 v127, v127, v35
	v_sub_f32_e32 v126, v126, v35
	v_sub_f32_e32 v125, v125, v35
	v_sub_f32_e32 v124, v124, v35
	v_sub_f32_e32 v123, v123, v35
	v_sub_f32_e32 v122, v122, v35
	v_sub_f32_e32 v121, v121, v35
	v_sub_f32_e32 v120, v120, v35
	v_sub_f32_e32 v119, v119, v35
	v_sub_f32_e32 v118, v118, v35
	v_sub_f32_e32 v117, v117, v35
	v_sub_f32_e32 v116, v116, v35
	v_sub_f32_e32 v115, v115, v35
	v_sub_f32_e32 v114, v114, v35
	v_sub_f32_e32 v145, v145, v35
	v_sub_f32_e32 v144, v144, v35
	v_sub_f32_e32 v143, v143, v35
	v_sub_f32_e32 v142, v142, v35
	v_sub_f32_e32 v141, v141, v35
	v_sub_f32_e32 v140, v140, v35
	v_sub_f32_e32 v139, v139, v35
	v_sub_f32_e32 v138, v138, v35
	v_sub_f32_e32 v137, v137, v35
	v_sub_f32_e32 v136, v136, v35
	v_sub_f32_e32 v135, v135, v35
	v_sub_f32_e32 v134, v134, v35
	v_sub_f32_e32 v133, v133, v35
	v_sub_f32_e32 v132, v132, v35
	v_sub_f32_e32 v131, v131, v35
	v_sub_f32_e32 v130, v130, v35
	v_pk_mul_f32 v[66:67], v[66:67], v[34:35] op_sel_hi:[1,0]
	s_waitcnt lgkmcnt(2)
	v_pk_mul_f32 v[32:33], v[32:33], v[42:43]
	v_pk_mul_f32 v[28:29], v[28:29], v[38:39]
	s_waitcnt lgkmcnt(1)
	v_pk_mul_f32 v[20:21], v[20:21], v[46:47]
	v_pk_mul_f32 v[30:31], v[30:31], v[40:41]
	v_pk_mul_f32 v[26:27], v[26:27], v[36:37]
	s_waitcnt lgkmcnt(0)
	v_pk_mul_f32 v[22:23], v[22:23], v[48:49]
	v_pk_mul_f32 v[18:19], v[18:19], v[44:45]
	v_pk_mul_f32 v[16:17], v[16:17], v[42:43]
	v_pk_mul_f32 v[12:13], v[12:13], v[38:39]
	v_pk_mul_f32 v[4:5], v[4:5], v[46:47]
	v_pk_mul_f32 v[14:15], v[14:15], v[40:41]
	v_pk_mul_f32 v[10:11], v[10:11], v[36:37]
	v_pk_mul_f32 v[6:7], v[6:7], v[48:49]
	v_pk_mul_f32 v[2:3], v[2:3], v[44:45]
	v_mov_b32_e32 v84, v82
	v_mov_b32_e32 v85, v82
	v_mov_b32_e32 v86, v82
	v_mov_b32_e32 v87, v82
	v_mov_b32_e32 v88, v82
	v_mov_b32_e32 v89, v82
	v_mov_b32_e32 v90, v82
	v_mov_b32_e32 v91, v82
	v_mov_b32_e32 v92, v82
	v_mov_b32_e32 v93, v82
	v_mov_b32_e32 v94, v82
	v_mov_b32_e32 v95, v82
	v_mov_b32_e32 v96, v82
	v_mov_b32_e32 v97, v82
	v_mov_b64_e32 v[34:35], v[82:83]
	v_pk_mul_f32 v[24:25], v[24:25], v[50:51]
	v_pk_mul_f32 v[8:9], v[8:9], v[50:51]
	v_mov_b32_e32 v112, v82
	v_mov_b32_e32 v111, v82
	v_mov_b32_e32 v110, v82
	v_mov_b32_e32 v109, v82
	v_mov_b32_e32 v108, v82
	v_mov_b32_e32 v107, v82
	v_mov_b32_e32 v106, v82
	v_mov_b32_e32 v105, v82
	v_mov_b32_e32 v104, v82
	v_mov_b32_e32 v103, v82
	v_mov_b32_e32 v102, v82
	v_mov_b32_e32 v101, v82
	v_mov_b32_e32 v100, v82
	v_mov_b32_e32 v99, v82
	v_mov_b32_e32 v98, v82
	v_mov_b64_e32 v[36:37], v[84:85]
	v_mov_b64_e32 v[38:39], v[86:87]
	v_mov_b64_e32 v[40:41], v[88:89]
	v_mov_b64_e32 v[42:43], v[90:91]
	v_mov_b64_e32 v[44:45], v[92:93]
	v_mov_b64_e32 v[46:47], v[94:95]
	v_mov_b64_e32 v[48:49], v[96:97]
